# token-0 shadow GEMM LDS fills: activation / gain loads issued 32 at a time in straight-line code (was 8-16 serialized load round trips per fill), same products and sum-of-squares order
# speedup vs baseline: 1.0263x; 1.0105x over previous
; template <int M> DEVI float shx(float v) { return __int_as_float(__builtin_amdgcn_ds_swizzle(__float_as_int(v), (M << 10) | 0x1f)); }
; DEVI void sk_gemm(const float* __restrict__ A, int lda, int K, const float* __restrict__ W, int N, const float* __restrict__ gain,
;                   bool use_rs, float* __restrict__ out, int ldo, int mode, unsigned char* lds, int wv, int bid, int nblk) {
;     ...
;         const int b = tid >> 5, j = tid & 31; float ss = 0.f;
; #pragma unroll 8
;         for (int k = j; k < kc; k += 32) { const float v = A[(size_t)b * lda + k0 + k]; ss += v * v; As[b * 1024 + k] = v * gain[k0 + k]; }
;         if (use_rs) { ss += shx<16>(ss); ss += shx<8>(ss); ss += shx<4>(ss); ss += shx<2>(ss); ss += shx<1>(ss); if (j == 0) rsS[b] = rsqrtf(ss / (float)K + 1e-6f); }
.LBB0_260:
	v_lshl_add_u64 v[14:15], v[2:3], 0, v[32:33]
	v_add_co_u32_e32 v14, vcc, 0x1f500000, v14
	v_lshl_add_u64 v[16:17], s[14:15], 0, v[32:33]
	s_nop 0
	v_addc_co_u32_e32 v15, vcc, 0, v15, vcc
	global_load_dword v186, v[14:15], off offset:0
	global_load_dword v187, v[14:15], off offset:128
	global_load_dword v188, v[14:15], off offset:256
	global_load_dword v189, v[14:15], off offset:384
	global_load_dword v190, v[14:15], off offset:512
	global_load_dword v191, v[14:15], off offset:640
	global_load_dword v192, v[14:15], off offset:768
	global_load_dword v193, v[14:15], off offset:896
	global_load_dword v194, v[14:15], off offset:1024
	global_load_dword v195, v[14:15], off offset:1152
	global_load_dword v196, v[14:15], off offset:1280
	global_load_dword v197, v[14:15], off offset:1408
	global_load_dword v198, v[14:15], off offset:1536
	global_load_dword v199, v[14:15], off offset:1664
	global_load_dword v200, v[14:15], off offset:1792
	global_load_dword v201, v[14:15], off offset:1920
	global_load_dword v202, v[16:17], off offset:0
	global_load_dword v203, v[16:17], off offset:128
	global_load_dword v204, v[16:17], off offset:256
	global_load_dword v205, v[16:17], off offset:384
	global_load_dword v206, v[16:17], off offset:512
	global_load_dword v207, v[16:17], off offset:640
	global_load_dword v208, v[16:17], off offset:768
	global_load_dword v209, v[16:17], off offset:896
	global_load_dword v210, v[16:17], off offset:1024
	global_load_dword v211, v[16:17], off offset:1152
	global_load_dword v212, v[16:17], off offset:1280
	global_load_dword v213, v[16:17], off offset:1408
	global_load_dword v214, v[16:17], off offset:1536
	global_load_dword v215, v[16:17], off offset:1664
	global_load_dword v216, v[16:17], off offset:1792
	global_load_dword v217, v[16:17], off offset:1920
	v_add_u32_e32 v218, 0x0, v12
	s_waitcnt vmcnt(14)
	v_fmac_f32_e32 v11, v186, v186
	v_mul_f32_e32 v186, v186, v202
	v_fmac_f32_e32 v11, v187, v187
	v_mul_f32_e32 v187, v187, v203
	ds_write2_b32 v218, v186, v187 offset1:32
	s_waitcnt vmcnt(12)
	v_fmac_f32_e32 v11, v188, v188
	v_mul_f32_e32 v188, v188, v204
	v_fmac_f32_e32 v11, v189, v189
	v_mul_f32_e32 v189, v189, v205
	ds_write2_b32 v218, v188, v189 offset0:64 offset1:96
	s_waitcnt vmcnt(10)
	v_fmac_f32_e32 v11, v190, v190
	v_mul_f32_e32 v190, v190, v206
	v_fmac_f32_e32 v11, v191, v191
	v_mul_f32_e32 v191, v191, v207
	ds_write2_b32 v218, v190, v191 offset0:128 offset1:160
	s_waitcnt vmcnt(8)
	v_fmac_f32_e32 v11, v192, v192
	v_mul_f32_e32 v192, v192, v208
	v_fmac_f32_e32 v11, v193, v193
	v_mul_f32_e32 v193, v193, v209
	ds_write2_b32 v218, v192, v193 offset0:192 offset1:224
	v_add_u32_e32 v218, 0x400, v12
	s_waitcnt vmcnt(6)
	v_fmac_f32_e32 v11, v194, v194
	v_mul_f32_e32 v194, v194, v210
	v_fmac_f32_e32 v11, v195, v195
	v_mul_f32_e32 v195, v195, v211
	ds_write2_b32 v218, v194, v195 offset1:32
	s_waitcnt vmcnt(4)
	v_fmac_f32_e32 v11, v196, v196
	v_mul_f32_e32 v196, v196, v212
	v_fmac_f32_e32 v11, v197, v197
	v_mul_f32_e32 v197, v197, v213
	ds_write2_b32 v218, v196, v197 offset0:64 offset1:96
	s_waitcnt vmcnt(2)
	v_fmac_f32_e32 v11, v198, v198
	v_mul_f32_e32 v198, v198, v214
	v_fmac_f32_e32 v11, v199, v199
	v_mul_f32_e32 v199, v199, v215
	ds_write2_b32 v218, v198, v199 offset0:128 offset1:160
	s_waitcnt vmcnt(0)
; template <int M> DEVI float shx(float v) { return __int_as_float(__builtin_amdgcn_ds_swizzle(__float_as_int(v), (M << 10) | 0x1f)); }
; DEVI void sk_gemm(const float* __restrict__ A, int lda, int K, const float* __restrict__ W, int N, const float* __restrict__ gain,
;                   bool use_rs, float* __restrict__ out, int ldo, int mode, unsigned char* lds, int wv, int bid, int nblk) {
;     ...
;         const int b = tid >> 5, j = tid & 31; float ss = 0.f;
; #pragma unroll 8
;         for (int k = j; k < kc; k += 32) { const float v = A[(size_t)b * lda + k0 + k]; ss += v * v; As[b * 1024 + k] = v * gain[k0 + k]; }
;         if (use_rs) { ss += shx<16>(ss); ss += shx<8>(ss); ss += shx<4>(ss); ss += shx<2>(ss); ss += shx<1>(ss); if (j == 0) rsS[b] = rsqrtf(ss / (float)K + 1e-6f); }
	v_fmac_f32_e32 v11, v200, v200
	v_mul_f32_e32 v200, v200, v216
	v_fmac_f32_e32 v11, v201, v201
	v_mul_f32_e32 v201, v201, v217
	ds_write2_b32 v218, v200, v201 offset0:192 offset1:224
	global_load_dword v186, v[14:15], off offset:2048
	global_load_dword v187, v[14:15], off offset:2176
	global_load_dword v188, v[14:15], off offset:2304
	global_load_dword v189, v[14:15], off offset:2432
	global_load_dword v190, v[14:15], off offset:2560
	global_load_dword v191, v[14:15], off offset:2688
	global_load_dword v192, v[14:15], off offset:2816
	global_load_dword v193, v[14:15], off offset:2944
	global_load_dword v194, v[14:15], off offset:3072
	global_load_dword v195, v[14:15], off offset:3200
	global_load_dword v196, v[14:15], off offset:3328
	global_load_dword v197, v[14:15], off offset:3456
	global_load_dword v198, v[14:15], off offset:3584
	global_load_dword v199, v[14:15], off offset:3712
	global_load_dword v200, v[14:15], off offset:3840
	global_load_dword v201, v[14:15], off offset:3968
	global_load_dword v202, v[16:17], off offset:2048
	global_load_dword v203, v[16:17], off offset:2176
	global_load_dword v204, v[16:17], off offset:2304
	global_load_dword v205, v[16:17], off offset:2432
	global_load_dword v206, v[16:17], off offset:2560
	global_load_dword v207, v[16:17], off offset:2688
	global_load_dword v208, v[16:17], off offset:2816
	global_load_dword v209, v[16:17], off offset:2944
	global_load_dword v210, v[16:17], off offset:3072
	global_load_dword v211, v[16:17], off offset:3200
	global_load_dword v212, v[16:17], off offset:3328
	global_load_dword v213, v[16:17], off offset:3456
	global_load_dword v214, v[16:17], off offset:3584
	global_load_dword v215, v[16:17], off offset:3712
	global_load_dword v216, v[16:17], off offset:3840
	global_load_dword v217, v[16:17], off offset:3968
	v_add_u32_e32 v218, 0x800, v12
	s_waitcnt vmcnt(14)
	v_fmac_f32_e32 v11, v186, v186
	v_mul_f32_e32 v186, v186, v202
	v_fmac_f32_e32 v11, v187, v187
	v_mul_f32_e32 v187, v187, v203
	ds_write2_b32 v218, v186, v187 offset1:32
	s_waitcnt vmcnt(12)
	v_fmac_f32_e32 v11, v188, v188
	v_mul_f32_e32 v188, v188, v204
	v_fmac_f32_e32 v11, v189, v189
	v_mul_f32_e32 v189, v189, v205
	ds_write2_b32 v218, v188, v189 offset0:64 offset1:96
	s_waitcnt vmcnt(10)
	v_fmac_f32_e32 v11, v190, v190
	v_mul_f32_e32 v190, v190, v206
	v_fmac_f32_e32 v11, v191, v191
	v_mul_f32_e32 v191, v191, v207
	ds_write2_b32 v218, v190, v191 offset0:128 offset1:160
	s_waitcnt vmcnt(8)
	v_fmac_f32_e32 v11, v192, v192
	v_mul_f32_e32 v192, v192, v208
	v_fmac_f32_e32 v11, v193, v193
	v_mul_f32_e32 v193, v193, v209
	ds_write2_b32 v218, v192, v193 offset0:192 offset1:224
	v_add_u32_e32 v218, 0xc00, v12
	s_waitcnt vmcnt(6)
	v_fmac_f32_e32 v11, v194, v194
	v_mul_f32_e32 v194, v194, v210
	v_fmac_f32_e32 v11, v195, v195
	v_mul_f32_e32 v195, v195, v211
	ds_write2_b32 v218, v194, v195 offset1:32
	s_waitcnt vmcnt(4)
	v_fmac_f32_e32 v11, v196, v196
	v_mul_f32_e32 v196, v196, v212
	v_fmac_f32_e32 v11, v197, v197
	v_mul_f32_e32 v197, v197, v213
	ds_write2_b32 v218, v196, v197 offset0:64 offset1:96
	s_waitcnt vmcnt(2)
	v_fmac_f32_e32 v11, v198, v198
	v_mul_f32_e32 v198, v198, v214
	v_fmac_f32_e32 v11, v199, v199
	v_mul_f32_e32 v199, v199, v215
	ds_write2_b32 v218, v198, v199 offset0:128 offset1:160
	s_waitcnt vmcnt(0)
	v_fmac_f32_e32 v11, v200, v200
	v_mul_f32_e32 v200, v200, v216
	v_fmac_f32_e32 v11, v201, v201
	v_mul_f32_e32 v201, v201, v217
	ds_write2_b32 v218, v200, v201 offset0:192 offset1:224
	s_or_b64 exec, exec, s[12:13]
	ds_swizzle_b32 v2, v11 offset:swizzle(SWAP,16)
	s_waitcnt lgkmcnt(0)
	v_add_f32_e32 v2, v11, v2
	ds_swizzle_b32 v3, v2 offset:swizzle(SWAP,8)
	s_waitcnt lgkmcnt(0)
	v_add_f32_e32 v2, v2, v3
	ds_swizzle_b32 v3, v2 offset:swizzle(SWAP,4)
	s_waitcnt lgkmcnt(0)
	v_add_f32_e32 v2, v2, v3
	ds_swizzle_b32 v3, v2 offset:swizzle(SWAP,2)
	s_waitcnt lgkmcnt(0)
	v_add_f32_e32 v2, v2, v3
	ds_swizzle_b32 v3, v2 offset:swizzle(SWAP,1)
	s_and_saveexec_b64 s[12:13], s[0:1]
	s_cbranch_execz .LBB0_263
	s_waitcnt lgkmcnt(0)
	v_add_f32_e32 v2, v2, v3
	v_fmamk_f32 v2, v2, 0x3a800000, v224
	v_mul_f32_e32 v3, 0x4b800000, v2
	v_cmp_gt_f32_e32 vcc, s77, v2
	s_nop 1
	v_cndmask_b32_e32 v2, v2, v3, vcc
	v_rsq_f32_e32 v2, v2
	s_nop 0
	v_mul_f32_e32 v3, 0x45800000, v2
	v_cndmask_b32_e32 v2, v2, v3, vcc
	ds_write_b32 v39, v2

; DEVI void sk_gemm(const float* __restrict__ A, int lda, int K, const float* __restrict__ W, int N, const float* __restrict__ gain,
;                   bool use_rs, float* __restrict__ out, int ldo, int mode, unsigned char* lds, int wv, int bid, int nblk) {
;     ...
;         for (int k = j; k < kc; k += 32) { const float v = A[(size_t)b * lda + k0 + k]; ss += v * v; As[b * 1024 + k] = v * gain[k0 + k]; }
.LBB0_422:
	v_lshl_add_u64 v[14:15], v[2:3], 0, v[32:33]
	v_add_co_u32_e32 v14, vcc, 0x1f500000, v14
	v_lshl_add_u64 v[16:17], s[12:13], 0, v[32:33]
	s_nop 0
	v_addc_co_u32_e32 v15, vcc, 0, v15, vcc
	global_load_dword v186, v[14:15], off offset:0
	global_load_dword v187, v[14:15], off offset:128
	global_load_dword v188, v[14:15], off offset:256
	global_load_dword v189, v[14:15], off offset:384
	global_load_dword v190, v[14:15], off offset:512
	global_load_dword v191, v[14:15], off offset:640
	global_load_dword v192, v[14:15], off offset:768
	global_load_dword v193, v[14:15], off offset:896
	global_load_dword v194, v[14:15], off offset:1024
	global_load_dword v195, v[14:15], off offset:1152
	global_load_dword v196, v[14:15], off offset:1280
	global_load_dword v197, v[14:15], off offset:1408
	global_load_dword v198, v[14:15], off offset:1536
	global_load_dword v199, v[14:15], off offset:1664
	global_load_dword v200, v[14:15], off offset:1792
	global_load_dword v201, v[14:15], off offset:1920
	global_load_dword v202, v[16:17], off offset:0
	global_load_dword v203, v[16:17], off offset:128
	global_load_dword v204, v[16:17], off offset:256
	global_load_dword v205, v[16:17], off offset:384
	global_load_dword v206, v[16:17], off offset:512
	global_load_dword v207, v[16:17], off offset:640
	global_load_dword v208, v[16:17], off offset:768
	global_load_dword v209, v[16:17], off offset:896
	global_load_dword v210, v[16:17], off offset:1024
	global_load_dword v211, v[16:17], off offset:1152
	global_load_dword v212, v[16:17], off offset:1280
	global_load_dword v213, v[16:17], off offset:1408
	global_load_dword v214, v[16:17], off offset:1536
	global_load_dword v215, v[16:17], off offset:1664
	global_load_dword v216, v[16:17], off offset:1792
	global_load_dword v217, v[16:17], off offset:1920
	v_add_u32_e32 v218, 0x0, v12
	s_waitcnt vmcnt(14)
	v_fmac_f32_e32 v11, v186, v186
	v_mul_f32_e32 v186, v186, v202
	v_fmac_f32_e32 v11, v187, v187
	v_mul_f32_e32 v187, v187, v203
	ds_write2_b32 v218, v186, v187 offset1:32
	s_waitcnt vmcnt(12)
	v_fmac_f32_e32 v11, v188, v188
	v_mul_f32_e32 v188, v188, v204
	v_fmac_f32_e32 v11, v189, v189
	v_mul_f32_e32 v189, v189, v205
	ds_write2_b32 v218, v188, v189 offset0:64 offset1:96
	s_waitcnt vmcnt(10)
	v_fmac_f32_e32 v11, v190, v190
	v_mul_f32_e32 v190, v190, v206
	v_fmac_f32_e32 v11, v191, v191
	v_mul_f32_e32 v191, v191, v207
	ds_write2_b32 v218, v190, v191 offset0:128 offset1:160
	s_waitcnt vmcnt(8)
	v_fmac_f32_e32 v11, v192, v192
	v_mul_f32_e32 v192, v192, v208
	v_fmac_f32_e32 v11, v193, v193
	v_mul_f32_e32 v193, v193, v209
	ds_write2_b32 v218, v192, v193 offset0:192 offset1:224
	v_add_u32_e32 v218, 0x400, v12
	s_waitcnt vmcnt(6)
	v_fmac_f32_e32 v11, v194, v194
	v_mul_f32_e32 v194, v194, v210
	v_fmac_f32_e32 v11, v195, v195
	v_mul_f32_e32 v195, v195, v211
	ds_write2_b32 v218, v194, v195 offset1:32
	s_waitcnt vmcnt(4)
	v_fmac_f32_e32 v11, v196, v196
	v_mul_f32_e32 v196, v196, v212
	v_fmac_f32_e32 v11, v197, v197
	v_mul_f32_e32 v197, v197, v213
	ds_write2_b32 v218, v196, v197 offset0:64 offset1:96
	s_waitcnt vmcnt(2)
	v_fmac_f32_e32 v11, v198, v198
	v_mul_f32_e32 v198, v198, v214
	v_fmac_f32_e32 v11, v199, v199
	v_mul_f32_e32 v199, v199, v215
	ds_write2_b32 v218, v198, v199 offset0:128 offset1:160
	s_waitcnt vmcnt(0)
; template <int M> DEVI float shx(float v) { return __int_as_float(__builtin_amdgcn_ds_swizzle(__float_as_int(v), (M << 10) | 0x1f)); }
; DEVI void sk_gemm(const float* __restrict__ A, int lda, int K, const float* __restrict__ W, int N, const float* __restrict__ gain,
;                   bool use_rs, float* __restrict__ out, int ldo, int mode, unsigned char* lds, int wv, int bid, int nblk) {
;     ...
;         const int b = tid >> 5, j = tid & 31; float ss = 0.f;
; #pragma unroll 8
;         for (int k = j; k < kc; k += 32) { const float v = A[(size_t)b * lda + k0 + k]; ss += v * v; As[b * 1024 + k] = v * gain[k0 + k]; }
;         if (use_rs) { ss += shx<16>(ss); ss += shx<8>(ss); ss += shx<4>(ss); ss += shx<2>(ss); ss += shx<1>(ss); if (j == 0) rsS[b] = rsqrtf(ss / (float)K + 1e-6f); }
	v_fmac_f32_e32 v11, v200, v200
	v_mul_f32_e32 v200, v200, v216
	v_fmac_f32_e32 v11, v201, v201
	v_mul_f32_e32 v201, v201, v217
	ds_write2_b32 v218, v200, v201 offset0:192 offset1:224
	global_load_dword v186, v[14:15], off offset:2048
	global_load_dword v187, v[14:15], off offset:2176
	global_load_dword v188, v[14:15], off offset:2304
	global_load_dword v189, v[14:15], off offset:2432
	global_load_dword v190, v[14:15], off offset:2560
	global_load_dword v191, v[14:15], off offset:2688
	global_load_dword v192, v[14:15], off offset:2816
	global_load_dword v193, v[14:15], off offset:2944
	global_load_dword v194, v[14:15], off offset:3072
	global_load_dword v195, v[14:15], off offset:3200
	global_load_dword v196, v[14:15], off offset:3328
	global_load_dword v197, v[14:15], off offset:3456
	global_load_dword v198, v[14:15], off offset:3584
	global_load_dword v199, v[14:15], off offset:3712
	global_load_dword v200, v[14:15], off offset:3840
	global_load_dword v201, v[14:15], off offset:3968
	global_load_dword v202, v[16:17], off offset:2048
	global_load_dword v203, v[16:17], off offset:2176
	global_load_dword v204, v[16:17], off offset:2304
	global_load_dword v205, v[16:17], off offset:2432
	global_load_dword v206, v[16:17], off offset:2560
	global_load_dword v207, v[16:17], off offset:2688
	global_load_dword v208, v[16:17], off offset:2816
	global_load_dword v209, v[16:17], off offset:2944
	global_load_dword v210, v[16:17], off offset:3072
	global_load_dword v211, v[16:17], off offset:3200
	global_load_dword v212, v[16:17], off offset:3328
	global_load_dword v213, v[16:17], off offset:3456
	global_load_dword v214, v[16:17], off offset:3584
	global_load_dword v215, v[16:17], off offset:3712
	global_load_dword v216, v[16:17], off offset:3840
	global_load_dword v217, v[16:17], off offset:3968
	v_add_u32_e32 v218, 0x800, v12
	s_waitcnt vmcnt(14)
	v_fmac_f32_e32 v11, v186, v186
	v_mul_f32_e32 v186, v186, v202
	v_fmac_f32_e32 v11, v187, v187
	v_mul_f32_e32 v187, v187, v203
	ds_write2_b32 v218, v186, v187 offset1:32
	s_waitcnt vmcnt(12)
	v_fmac_f32_e32 v11, v188, v188
	v_mul_f32_e32 v188, v188, v204
	v_fmac_f32_e32 v11, v189, v189
	v_mul_f32_e32 v189, v189, v205
	ds_write2_b32 v218, v188, v189 offset0:64 offset1:96
	s_waitcnt vmcnt(10)
	v_fmac_f32_e32 v11, v190, v190
	v_mul_f32_e32 v190, v190, v206
	v_fmac_f32_e32 v11, v191, v191
	v_mul_f32_e32 v191, v191, v207
	ds_write2_b32 v218, v190, v191 offset0:128 offset1:160
	s_waitcnt vmcnt(8)
	v_fmac_f32_e32 v11, v192, v192
	v_mul_f32_e32 v192, v192, v208
	v_fmac_f32_e32 v11, v193, v193
	v_mul_f32_e32 v193, v193, v209
	ds_write2_b32 v218, v192, v193 offset0:192 offset1:224
	v_add_u32_e32 v218, 0xc00, v12
	s_waitcnt vmcnt(6)
	v_fmac_f32_e32 v11, v194, v194
	v_mul_f32_e32 v194, v194, v210
	v_fmac_f32_e32 v11, v195, v195
	v_mul_f32_e32 v195, v195, v211
	ds_write2_b32 v218, v194, v195 offset1:32
	s_waitcnt vmcnt(4)
	v_fmac_f32_e32 v11, v196, v196
	v_mul_f32_e32 v196, v196, v212
	v_fmac_f32_e32 v11, v197, v197
	v_mul_f32_e32 v197, v197, v213
	ds_write2_b32 v218, v196, v197 offset0:64 offset1:96
	s_waitcnt vmcnt(2)
	v_fmac_f32_e32 v11, v198, v198
	v_mul_f32_e32 v198, v198, v214
	v_fmac_f32_e32 v11, v199, v199
	v_mul_f32_e32 v199, v199, v215
	ds_write2_b32 v218, v198, v199 offset0:128 offset1:160
	s_waitcnt vmcnt(0)
	v_fmac_f32_e32 v11, v200, v200
	v_mul_f32_e32 v200, v200, v216
	v_fmac_f32_e32 v11, v201, v201
	v_mul_f32_e32 v201, v201, v217
	ds_write2_b32 v218, v200, v201 offset0:192 offset1:224
	s_or_b64 exec, exec, s[10:11]
	ds_swizzle_b32 v2, v11 offset:swizzle(SWAP,16)
	s_waitcnt lgkmcnt(0)
	v_add_f32_e32 v2, v11, v2
	ds_swizzle_b32 v3, v2 offset:swizzle(SWAP,8)
	s_waitcnt lgkmcnt(0)
	v_add_f32_e32 v2, v2, v3
	ds_swizzle_b32 v3, v2 offset:swizzle(SWAP,4)
	s_waitcnt lgkmcnt(0)
	v_add_f32_e32 v2, v2, v3
	ds_swizzle_b32 v3, v2 offset:swizzle(SWAP,2)
	s_waitcnt lgkmcnt(0)
	v_add_f32_e32 v2, v2, v3
	ds_swizzle_b32 v3, v2 offset:swizzle(SWAP,1)
	s_and_saveexec_b64 s[10:11], s[0:1]
	s_cbranch_execz .LBB0_425
	s_waitcnt lgkmcnt(0)
	v_add_f32_e32 v2, v2, v3
	v_fmamk_f32 v2, v2, 0x3a800000, v224
	v_mul_f32_e32 v3, 0x4b800000, v2
	v_cmp_gt_f32_e32 vcc, s77, v2
	s_nop 1
	v_cndmask_b32_e32 v2, v2, v3, vcc
	v_rsq_f32_e32 v2, v2
	s_nop 0
	v_mul_f32_e32 v3, 0x45800000, v2
	v_cndmask_b32_e32 v2, v2, v3, vcc
	ds_write_b32 v39, v2

; DEVI void sk_gemm(const float* __restrict__ A, int lda, int K, const float* __restrict__ W, int N, const float* __restrict__ gain,
;                   bool use_rs, float* __restrict__ out, int ldo, int mode, unsigned char* lds, int wv, int bid, int nblk) {
;     ...
;         for (int k = j; k < kc; k += 32) { const float v = A[(size_t)b * lda + k0 + k]; ss += v * v; As[b * 1024 + k] = v * gain[k0 + k]; }
.LBB0_1053:
	v_lshl_add_u64 v[14:15], v[2:3], 0, v[32:33]
	v_add_co_u32_e32 v14, vcc, 0x1f500000, v14
	v_lshl_add_u64 v[16:17], s[18:19], 0, v[32:33]
	s_nop 0
	v_addc_co_u32_e32 v15, vcc, 0, v15, vcc
	global_load_dword v186, v[14:15], off offset:0
	global_load_dword v187, v[14:15], off offset:128
	global_load_dword v188, v[14:15], off offset:256
	global_load_dword v189, v[14:15], off offset:384
	global_load_dword v190, v[14:15], off offset:512
	global_load_dword v191, v[14:15], off offset:640
	global_load_dword v192, v[14:15], off offset:768
	global_load_dword v193, v[14:15], off offset:896
	global_load_dword v194, v[14:15], off offset:1024
	global_load_dword v195, v[14:15], off offset:1152
	global_load_dword v196, v[14:15], off offset:1280
	global_load_dword v197, v[14:15], off offset:1408
	global_load_dword v198, v[14:15], off offset:1536
	global_load_dword v199, v[14:15], off offset:1664
	global_load_dword v200, v[14:15], off offset:1792
	global_load_dword v201, v[14:15], off offset:1920
	global_load_dword v202, v[16:17], off offset:0
	global_load_dword v203, v[16:17], off offset:128
	global_load_dword v204, v[16:17], off offset:256
	global_load_dword v205, v[16:17], off offset:384
	global_load_dword v206, v[16:17], off offset:512
	global_load_dword v207, v[16:17], off offset:640
	global_load_dword v208, v[16:17], off offset:768
	global_load_dword v209, v[16:17], off offset:896
	global_load_dword v210, v[16:17], off offset:1024
	global_load_dword v211, v[16:17], off offset:1152
	global_load_dword v212, v[16:17], off offset:1280
	global_load_dword v213, v[16:17], off offset:1408
	global_load_dword v214, v[16:17], off offset:1536
	global_load_dword v215, v[16:17], off offset:1664
	global_load_dword v216, v[16:17], off offset:1792
	global_load_dword v217, v[16:17], off offset:1920
	v_add_u32_e32 v218, 0x0, v12
	s_waitcnt vmcnt(14)
	v_fmac_f32_e32 v11, v186, v186
	v_mul_f32_e32 v186, v186, v202
	v_fmac_f32_e32 v11, v187, v187
	v_mul_f32_e32 v187, v187, v203
	ds_write2_b32 v218, v186, v187 offset1:32
	s_waitcnt vmcnt(12)
	v_fmac_f32_e32 v11, v188, v188
	v_mul_f32_e32 v188, v188, v204
	v_fmac_f32_e32 v11, v189, v189
	v_mul_f32_e32 v189, v189, v205
	ds_write2_b32 v218, v188, v189 offset0:64 offset1:96
	s_waitcnt vmcnt(10)
	v_fmac_f32_e32 v11, v190, v190
	v_mul_f32_e32 v190, v190, v206
	v_fmac_f32_e32 v11, v191, v191
	v_mul_f32_e32 v191, v191, v207
	ds_write2_b32 v218, v190, v191 offset0:128 offset1:160
	s_waitcnt vmcnt(8)
	v_fmac_f32_e32 v11, v192, v192
	v_mul_f32_e32 v192, v192, v208
	v_fmac_f32_e32 v11, v193, v193
	v_mul_f32_e32 v193, v193, v209
	ds_write2_b32 v218, v192, v193 offset0:192 offset1:224
	v_add_u32_e32 v218, 0x400, v12
	s_waitcnt vmcnt(6)
	v_fmac_f32_e32 v11, v194, v194
	v_mul_f32_e32 v194, v194, v210
	v_fmac_f32_e32 v11, v195, v195
	v_mul_f32_e32 v195, v195, v211
	ds_write2_b32 v218, v194, v195 offset1:32
	s_waitcnt vmcnt(4)
	v_fmac_f32_e32 v11, v196, v196
	v_mul_f32_e32 v196, v196, v212
	v_fmac_f32_e32 v11, v197, v197
	v_mul_f32_e32 v197, v197, v213
	ds_write2_b32 v218, v196, v197 offset0:64 offset1:96
	s_waitcnt vmcnt(2)
	v_fmac_f32_e32 v11, v198, v198
	v_mul_f32_e32 v198, v198, v214
	v_fmac_f32_e32 v11, v199, v199
	v_mul_f32_e32 v199, v199, v215
	ds_write2_b32 v218, v198, v199 offset0:128 offset1:160
	s_waitcnt vmcnt(0)
; template <int M> DEVI float shx(float v) { return __int_as_float(__builtin_amdgcn_ds_swizzle(__float_as_int(v), (M << 10) | 0x1f)); }
; DEVI void sk_gemm(const float* __restrict__ A, int lda, int K, const float* __restrict__ W, int N, const float* __restrict__ gain,
;                   bool use_rs, float* __restrict__ out, int ldo, int mode, unsigned char* lds, int wv, int bid, int nblk) {
;     ...
;         const int b = tid >> 5, j = tid & 31; float ss = 0.f;
; #pragma unroll 8
;         for (int k = j; k < kc; k += 32) { const float v = A[(size_t)b * lda + k0 + k]; ss += v * v; As[b * 1024 + k] = v * gain[k0 + k]; }
;         if (use_rs) { ss += shx<16>(ss); ss += shx<8>(ss); ss += shx<4>(ss); ss += shx<2>(ss); ss += shx<1>(ss); if (j == 0) rsS[b] = rsqrtf(ss / (float)K + 1e-6f); }
	v_fmac_f32_e32 v11, v200, v200
	v_mul_f32_e32 v200, v200, v216
	v_fmac_f32_e32 v11, v201, v201
	v_mul_f32_e32 v201, v201, v217
	ds_write2_b32 v218, v200, v201 offset0:192 offset1:224
	global_load_dword v186, v[14:15], off offset:2048
	global_load_dword v187, v[14:15], off offset:2176
	global_load_dword v188, v[14:15], off offset:2304
	global_load_dword v189, v[14:15], off offset:2432
	global_load_dword v190, v[14:15], off offset:2560
	global_load_dword v191, v[14:15], off offset:2688
	global_load_dword v192, v[14:15], off offset:2816
	global_load_dword v193, v[14:15], off offset:2944
	global_load_dword v194, v[14:15], off offset:3072
	global_load_dword v195, v[14:15], off offset:3200
	global_load_dword v196, v[14:15], off offset:3328
	global_load_dword v197, v[14:15], off offset:3456
	global_load_dword v198, v[14:15], off offset:3584
	global_load_dword v199, v[14:15], off offset:3712
	global_load_dword v200, v[14:15], off offset:3840
	global_load_dword v201, v[14:15], off offset:3968
	global_load_dword v202, v[16:17], off offset:2048
	global_load_dword v203, v[16:17], off offset:2176
	global_load_dword v204, v[16:17], off offset:2304
	global_load_dword v205, v[16:17], off offset:2432
	global_load_dword v206, v[16:17], off offset:2560
	global_load_dword v207, v[16:17], off offset:2688
	global_load_dword v208, v[16:17], off offset:2816
	global_load_dword v209, v[16:17], off offset:2944
	global_load_dword v210, v[16:17], off offset:3072
	global_load_dword v211, v[16:17], off offset:3200
	global_load_dword v212, v[16:17], off offset:3328
	global_load_dword v213, v[16:17], off offset:3456
	global_load_dword v214, v[16:17], off offset:3584
	global_load_dword v215, v[16:17], off offset:3712
	global_load_dword v216, v[16:17], off offset:3840
	global_load_dword v217, v[16:17], off offset:3968
	v_add_u32_e32 v218, 0x800, v12
	s_waitcnt vmcnt(14)
	v_fmac_f32_e32 v11, v186, v186
	v_mul_f32_e32 v186, v186, v202
	v_fmac_f32_e32 v11, v187, v187
	v_mul_f32_e32 v187, v187, v203
	ds_write2_b32 v218, v186, v187 offset1:32
	s_waitcnt vmcnt(12)
	v_fmac_f32_e32 v11, v188, v188
	v_mul_f32_e32 v188, v188, v204
	v_fmac_f32_e32 v11, v189, v189
	v_mul_f32_e32 v189, v189, v205
	ds_write2_b32 v218, v188, v189 offset0:64 offset1:96
	s_waitcnt vmcnt(10)
	v_fmac_f32_e32 v11, v190, v190
	v_mul_f32_e32 v190, v190, v206
	v_fmac_f32_e32 v11, v191, v191
	v_mul_f32_e32 v191, v191, v207
	ds_write2_b32 v218, v190, v191 offset0:128 offset1:160
	s_waitcnt vmcnt(8)
	v_fmac_f32_e32 v11, v192, v192
	v_mul_f32_e32 v192, v192, v208
	v_fmac_f32_e32 v11, v193, v193
	v_mul_f32_e32 v193, v193, v209
	ds_write2_b32 v218, v192, v193 offset0:192 offset1:224
	v_add_u32_e32 v218, 0xc00, v12
	s_waitcnt vmcnt(6)
	v_fmac_f32_e32 v11, v194, v194
	v_mul_f32_e32 v194, v194, v210
	v_fmac_f32_e32 v11, v195, v195
	v_mul_f32_e32 v195, v195, v211
	ds_write2_b32 v218, v194, v195 offset1:32
	s_waitcnt vmcnt(4)
	v_fmac_f32_e32 v11, v196, v196
	v_mul_f32_e32 v196, v196, v212
	v_fmac_f32_e32 v11, v197, v197
	v_mul_f32_e32 v197, v197, v213
	ds_write2_b32 v218, v196, v197 offset0:64 offset1:96
	s_waitcnt vmcnt(2)
	v_fmac_f32_e32 v11, v198, v198
	v_mul_f32_e32 v198, v198, v214
	v_fmac_f32_e32 v11, v199, v199
	v_mul_f32_e32 v199, v199, v215
	ds_write2_b32 v218, v198, v199 offset0:128 offset1:160
	s_waitcnt vmcnt(0)
	v_fmac_f32_e32 v11, v200, v200
	v_mul_f32_e32 v200, v200, v216
	v_fmac_f32_e32 v11, v201, v201
	v_mul_f32_e32 v201, v201, v217
	ds_write2_b32 v218, v200, v201 offset0:192 offset1:224
	s_or_b64 exec, exec, s[14:15]
	ds_swizzle_b32 v2, v11 offset:swizzle(SWAP,16)
	s_waitcnt lgkmcnt(0)
	v_add_f32_e32 v2, v11, v2
	ds_swizzle_b32 v3, v2 offset:swizzle(SWAP,8)
	s_waitcnt lgkmcnt(0)
	v_add_f32_e32 v2, v2, v3
	ds_swizzle_b32 v3, v2 offset:swizzle(SWAP,4)
	s_waitcnt lgkmcnt(0)
	v_add_f32_e32 v2, v2, v3
	ds_swizzle_b32 v3, v2 offset:swizzle(SWAP,2)
	s_waitcnt lgkmcnt(0)
	v_add_f32_e32 v2, v2, v3
	ds_swizzle_b32 v3, v2 offset:swizzle(SWAP,1)
	s_and_saveexec_b64 s[14:15], s[0:1]
	s_cbranch_execz .LBB0_1056
	s_waitcnt lgkmcnt(0)
	v_add_f32_e32 v2, v2, v3
	v_fmamk_f32 v2, v2, 0x3a800000, v224
	v_mul_f32_e32 v3, 0x4b800000, v2
	v_cmp_gt_f32_e32 vcc, s77, v2
	s_nop 1
	v_cndmask_b32_e32 v2, v2, v3, vcc
	v_rsq_f32_e32 v2, v2
	s_nop 0
	v_mul_f32_e32 v3, 0x45800000, v2
	v_cndmask_b32_e32 v2, v2, v3, vcc
	ds_write_b32 v39, v2

; template <int M> DEVI float shx(float v) { return __int_as_float(__builtin_amdgcn_ds_swizzle(__float_as_int(v), (M << 10) | 0x1f)); }
; DEVI void sk_gemm(const float* __restrict__ A, int lda, int K, const float* __restrict__ W, int N, const float* __restrict__ gain,
;                   bool use_rs, float* __restrict__ out, int ldo, int mode, unsigned char* lds, int wv, int bid, int nblk) {
;     ...
;         const int b = tid >> 5, j = tid & 31; float ss = 0.f;
; #pragma unroll 8
;         for (int k = j; k < kc; k += 32) { const float v = A[(size_t)b * lda + k0 + k]; ss += v * v; As[b * 1024 + k] = v * gain[k0 + k]; }
;         if (use_rs) { ss += shx<16>(ss); ss += shx<8>(ss); ss += shx<4>(ss); ss += shx<2>(ss); ss += shx<1>(ss); if (j == 0) rsS[b] = rsqrtf(ss / (float)K + 1e-6f); }
.LBB0_1810:
	v_lshl_add_u64 v[14:15], v[2:3], 0, v[32:33]
	v_add_co_u32_e32 v14, vcc, 0x1f500000, v14
	v_lshl_add_u64 v[16:17], s[20:21], 0, v[32:33]
	s_nop 0
	v_addc_co_u32_e32 v15, vcc, 0, v15, vcc
	global_load_dword v186, v[14:15], off offset:0
	global_load_dword v187, v[14:15], off offset:128
	global_load_dword v188, v[14:15], off offset:256
	global_load_dword v189, v[14:15], off offset:384
	global_load_dword v190, v[14:15], off offset:512
	global_load_dword v191, v[14:15], off offset:640
	global_load_dword v192, v[14:15], off offset:768
	global_load_dword v193, v[14:15], off offset:896
	global_load_dword v194, v[14:15], off offset:1024
	global_load_dword v195, v[14:15], off offset:1152
	global_load_dword v196, v[14:15], off offset:1280
	global_load_dword v197, v[14:15], off offset:1408
	global_load_dword v198, v[14:15], off offset:1536
	global_load_dword v199, v[14:15], off offset:1664
	global_load_dword v200, v[14:15], off offset:1792
	global_load_dword v201, v[14:15], off offset:1920
	global_load_dword v202, v[16:17], off offset:0
	global_load_dword v203, v[16:17], off offset:128
	global_load_dword v204, v[16:17], off offset:256
	global_load_dword v205, v[16:17], off offset:384
	global_load_dword v206, v[16:17], off offset:512
	global_load_dword v207, v[16:17], off offset:640
	global_load_dword v208, v[16:17], off offset:768
	global_load_dword v209, v[16:17], off offset:896
	global_load_dword v210, v[16:17], off offset:1024
	global_load_dword v211, v[16:17], off offset:1152
	global_load_dword v212, v[16:17], off offset:1280
	global_load_dword v213, v[16:17], off offset:1408
	global_load_dword v214, v[16:17], off offset:1536
	global_load_dword v215, v[16:17], off offset:1664
	global_load_dword v216, v[16:17], off offset:1792
	global_load_dword v217, v[16:17], off offset:1920
	v_add_u32_e32 v218, 0x0, v12
	s_waitcnt vmcnt(14)
	v_fmac_f32_e32 v11, v186, v186
	v_mul_f32_e32 v186, v186, v202
	v_fmac_f32_e32 v11, v187, v187
	v_mul_f32_e32 v187, v187, v203
	ds_write2_b32 v218, v186, v187 offset1:32
	s_waitcnt vmcnt(12)
	v_fmac_f32_e32 v11, v188, v188
	v_mul_f32_e32 v188, v188, v204
	v_fmac_f32_e32 v11, v189, v189
	v_mul_f32_e32 v189, v189, v205
	ds_write2_b32 v218, v188, v189 offset0:64 offset1:96
	s_waitcnt vmcnt(10)
	v_fmac_f32_e32 v11, v190, v190
	v_mul_f32_e32 v190, v190, v206
	v_fmac_f32_e32 v11, v191, v191
	v_mul_f32_e32 v191, v191, v207
	ds_write2_b32 v218, v190, v191 offset0:128 offset1:160
	s_waitcnt vmcnt(8)
	v_fmac_f32_e32 v11, v192, v192
	v_mul_f32_e32 v192, v192, v208
	v_fmac_f32_e32 v11, v193, v193
	v_mul_f32_e32 v193, v193, v209
	ds_write2_b32 v218, v192, v193 offset0:192 offset1:224
	v_add_u32_e32 v218, 0x400, v12
	s_waitcnt vmcnt(6)
	v_fmac_f32_e32 v11, v194, v194
	v_mul_f32_e32 v194, v194, v210
	v_fmac_f32_e32 v11, v195, v195
	v_mul_f32_e32 v195, v195, v211
	ds_write2_b32 v218, v194, v195 offset1:32
	s_waitcnt vmcnt(4)
	v_fmac_f32_e32 v11, v196, v196
	v_mul_f32_e32 v196, v196, v212
	v_fmac_f32_e32 v11, v197, v197
	v_mul_f32_e32 v197, v197, v213
	ds_write2_b32 v218, v196, v197 offset0:64 offset1:96
	s_waitcnt vmcnt(2)
	v_fmac_f32_e32 v11, v198, v198
	v_mul_f32_e32 v198, v198, v214
	v_fmac_f32_e32 v11, v199, v199
	v_mul_f32_e32 v199, v199, v215
	ds_write2_b32 v218, v198, v199 offset0:128 offset1:160
	s_waitcnt vmcnt(0)
; template <int M> DEVI float shx(float v) { return __int_as_float(__builtin_amdgcn_ds_swizzle(__float_as_int(v), (M << 10) | 0x1f)); }
; DEVI void sk_gemm(const float* __restrict__ A, int lda, int K, const float* __restrict__ W, int N, const float* __restrict__ gain,
;                   bool use_rs, float* __restrict__ out, int ldo, int mode, unsigned char* lds, int wv, int bid, int nblk) {
;     ...
;         const int b = tid >> 5, j = tid & 31; float ss = 0.f;
; #pragma unroll 8
;         for (int k = j; k < kc; k += 32) { const float v = A[(size_t)b * lda + k0 + k]; ss += v * v; As[b * 1024 + k] = v * gain[k0 + k]; }
;         if (use_rs) { ss += shx<16>(ss); ss += shx<8>(ss); ss += shx<4>(ss); ss += shx<2>(ss); ss += shx<1>(ss); if (j == 0) rsS[b] = rsqrtf(ss / (float)K + 1e-6f); }
	v_fmac_f32_e32 v11, v200, v200
	v_mul_f32_e32 v200, v200, v216
	v_fmac_f32_e32 v11, v201, v201
	v_mul_f32_e32 v201, v201, v217
	ds_write2_b32 v218, v200, v201 offset0:192 offset1:224
	global_load_dword v186, v[14:15], off offset:2048
	global_load_dword v187, v[14:15], off offset:2176
	global_load_dword v188, v[14:15], off offset:2304
	global_load_dword v189, v[14:15], off offset:2432
	global_load_dword v190, v[14:15], off offset:2560
	global_load_dword v191, v[14:15], off offset:2688
	global_load_dword v192, v[14:15], off offset:2816
	global_load_dword v193, v[14:15], off offset:2944
	global_load_dword v194, v[14:15], off offset:3072
	global_load_dword v195, v[14:15], off offset:3200
	global_load_dword v196, v[14:15], off offset:3328
	global_load_dword v197, v[14:15], off offset:3456
	global_load_dword v198, v[14:15], off offset:3584
	global_load_dword v199, v[14:15], off offset:3712
	global_load_dword v200, v[14:15], off offset:3840
	global_load_dword v201, v[14:15], off offset:3968
	global_load_dword v202, v[16:17], off offset:2048
	global_load_dword v203, v[16:17], off offset:2176
	global_load_dword v204, v[16:17], off offset:2304
	global_load_dword v205, v[16:17], off offset:2432
	global_load_dword v206, v[16:17], off offset:2560
	global_load_dword v207, v[16:17], off offset:2688
	global_load_dword v208, v[16:17], off offset:2816
	global_load_dword v209, v[16:17], off offset:2944
	global_load_dword v210, v[16:17], off offset:3072
	global_load_dword v211, v[16:17], off offset:3200
	global_load_dword v212, v[16:17], off offset:3328
	global_load_dword v213, v[16:17], off offset:3456
	global_load_dword v214, v[16:17], off offset:3584
	global_load_dword v215, v[16:17], off offset:3712
	global_load_dword v216, v[16:17], off offset:3840
	global_load_dword v217, v[16:17], off offset:3968
	v_add_u32_e32 v218, 0x800, v12
	s_waitcnt vmcnt(14)
	v_fmac_f32_e32 v11, v186, v186
	v_mul_f32_e32 v186, v186, v202
	v_fmac_f32_e32 v11, v187, v187
	v_mul_f32_e32 v187, v187, v203
	ds_write2_b32 v218, v186, v187 offset1:32
	s_waitcnt vmcnt(12)
	v_fmac_f32_e32 v11, v188, v188
	v_mul_f32_e32 v188, v188, v204
	v_fmac_f32_e32 v11, v189, v189
	v_mul_f32_e32 v189, v189, v205
	ds_write2_b32 v218, v188, v189 offset0:64 offset1:96
	s_waitcnt vmcnt(10)
	v_fmac_f32_e32 v11, v190, v190
	v_mul_f32_e32 v190, v190, v206
	v_fmac_f32_e32 v11, v191, v191
	v_mul_f32_e32 v191, v191, v207
	ds_write2_b32 v218, v190, v191 offset0:128 offset1:160
	s_waitcnt vmcnt(8)
	v_fmac_f32_e32 v11, v192, v192
	v_mul_f32_e32 v192, v192, v208
	v_fmac_f32_e32 v11, v193, v193
	v_mul_f32_e32 v193, v193, v209
	ds_write2_b32 v218, v192, v193 offset0:192 offset1:224
	v_add_u32_e32 v218, 0xc00, v12
	s_waitcnt vmcnt(6)
	v_fmac_f32_e32 v11, v194, v194
	v_mul_f32_e32 v194, v194, v210
	v_fmac_f32_e32 v11, v195, v195
	v_mul_f32_e32 v195, v195, v211
	ds_write2_b32 v218, v194, v195 offset1:32
	s_waitcnt vmcnt(4)
	v_fmac_f32_e32 v11, v196, v196
	v_mul_f32_e32 v196, v196, v212
	v_fmac_f32_e32 v11, v197, v197
	v_mul_f32_e32 v197, v197, v213
	ds_write2_b32 v218, v196, v197 offset0:64 offset1:96
	s_waitcnt vmcnt(2)
	v_fmac_f32_e32 v11, v198, v198
	v_mul_f32_e32 v198, v198, v214
	v_fmac_f32_e32 v11, v199, v199
	v_mul_f32_e32 v199, v199, v215
	ds_write2_b32 v218, v198, v199 offset0:128 offset1:160
	s_waitcnt vmcnt(0)
	v_fmac_f32_e32 v11, v200, v200
	v_mul_f32_e32 v200, v200, v216
	v_fmac_f32_e32 v11, v201, v201
	v_mul_f32_e32 v201, v201, v217
	ds_write2_b32 v218, v200, v201 offset0:192 offset1:224
	s_or_b64 exec, exec, s[16:17]
	ds_swizzle_b32 v2, v11 offset:swizzle(SWAP,16)
	s_waitcnt lgkmcnt(0)
	v_add_f32_e32 v2, v11, v2
	ds_swizzle_b32 v3, v2 offset:swizzle(SWAP,8)
	s_waitcnt lgkmcnt(0)
	v_add_f32_e32 v2, v2, v3
	ds_swizzle_b32 v3, v2 offset:swizzle(SWAP,4)
	s_waitcnt lgkmcnt(0)
	v_add_f32_e32 v2, v2, v3
	ds_swizzle_b32 v3, v2 offset:swizzle(SWAP,2)
	s_waitcnt lgkmcnt(0)
	v_add_f32_e32 v2, v2, v3
	ds_swizzle_b32 v3, v2 offset:swizzle(SWAP,1)
	s_and_saveexec_b64 s[16:17], s[4:5]
	s_cbranch_execz .LBB0_1813
	s_waitcnt lgkmcnt(0)
	v_add_f32_e32 v2, v2, v3
	v_fmamk_f32 v2, v2, 0x3a800000, v224
	v_mul_f32_e32 v3, 0x4b800000, v2
	v_cmp_gt_f32_e32 vcc, s77, v2
	s_nop 1
	v_cndmask_b32_e32 v2, v2, v3, vcc
	v_rsq_f32_e32 v2, v2
	s_nop 0
	v_mul_f32_e32 v3, 0x45800000, v2
	v_cndmask_b32_e32 v2, v2, v3, vcc
	ds_write_b32 v39, v2

; template <int M> DEVI float shx(float v) { return __int_as_float(__builtin_amdgcn_ds_swizzle(__float_as_int(v), (M << 10) | 0x1f)); }
; DEVI void sk_gemm(const float* __restrict__ A, int lda, int K, const float* __restrict__ W, int N, const float* __restrict__ gain,
;                   bool use_rs, float* __restrict__ out, int ldo, int mode, unsigned char* lds, int wv, int bid, int nblk) {
;     ...
;         const int b = tid >> 5, j = tid & 31; float ss = 0.f;
; #pragma unroll 8
;         for (int k = j; k < kc; k += 32) { const float v = A[(size_t)b * lda + k0 + k]; ss += v * v; As[b * 1024 + k] = v * gain[k0 + k]; }
;         if (use_rs) { ss += shx<16>(ss); ss += shx<8>(ss); ss += shx<4>(ss); ss += shx<2>(ss); ss += shx<1>(ss); if (j == 0) rsS[b] = rsqrtf(ss / (float)K + 1e-6f); }
.LBB0_1919:
	v_lshl_add_u64 v[14:15], v[2:3], 0, v[32:33]
	v_add_co_u32_e32 v14, vcc, 0x1f500000, v14
	v_lshl_add_u64 v[16:17], s[16:17], 0, v[32:33]
	s_nop 0
	v_addc_co_u32_e32 v15, vcc, 0, v15, vcc
	global_load_dword v186, v[14:15], off offset:0
	global_load_dword v187, v[14:15], off offset:128
	global_load_dword v188, v[14:15], off offset:256
	global_load_dword v189, v[14:15], off offset:384
	global_load_dword v190, v[14:15], off offset:512
	global_load_dword v191, v[14:15], off offset:640
	global_load_dword v192, v[14:15], off offset:768
	global_load_dword v193, v[14:15], off offset:896
	global_load_dword v194, v[14:15], off offset:1024
	global_load_dword v195, v[14:15], off offset:1152
	global_load_dword v196, v[14:15], off offset:1280
	global_load_dword v197, v[14:15], off offset:1408
	global_load_dword v198, v[14:15], off offset:1536
	global_load_dword v199, v[14:15], off offset:1664
	global_load_dword v200, v[14:15], off offset:1792
	global_load_dword v201, v[14:15], off offset:1920
	global_load_dword v202, v[16:17], off offset:0
	global_load_dword v203, v[16:17], off offset:128
	global_load_dword v204, v[16:17], off offset:256
	global_load_dword v205, v[16:17], off offset:384
	global_load_dword v206, v[16:17], off offset:512
	global_load_dword v207, v[16:17], off offset:640
	global_load_dword v208, v[16:17], off offset:768
	global_load_dword v209, v[16:17], off offset:896
	global_load_dword v210, v[16:17], off offset:1024
	global_load_dword v211, v[16:17], off offset:1152
	global_load_dword v212, v[16:17], off offset:1280
	global_load_dword v213, v[16:17], off offset:1408
	global_load_dword v214, v[16:17], off offset:1536
	global_load_dword v215, v[16:17], off offset:1664
	global_load_dword v216, v[16:17], off offset:1792
	global_load_dword v217, v[16:17], off offset:1920
	v_add_u32_e32 v218, 0x0, v12
	s_waitcnt vmcnt(14)
	v_fmac_f32_e32 v11, v186, v186
	v_mul_f32_e32 v186, v186, v202
	v_fmac_f32_e32 v11, v187, v187
	v_mul_f32_e32 v187, v187, v203
	ds_write2_b32 v218, v186, v187 offset1:32
	s_waitcnt vmcnt(12)
	v_fmac_f32_e32 v11, v188, v188
	v_mul_f32_e32 v188, v188, v204
	v_fmac_f32_e32 v11, v189, v189
	v_mul_f32_e32 v189, v189, v205
	ds_write2_b32 v218, v188, v189 offset0:64 offset1:96
	s_waitcnt vmcnt(10)
	v_fmac_f32_e32 v11, v190, v190
	v_mul_f32_e32 v190, v190, v206
	v_fmac_f32_e32 v11, v191, v191
	v_mul_f32_e32 v191, v191, v207
	ds_write2_b32 v218, v190, v191 offset0:128 offset1:160
	s_waitcnt vmcnt(8)
	v_fmac_f32_e32 v11, v192, v192
	v_mul_f32_e32 v192, v192, v208
	v_fmac_f32_e32 v11, v193, v193
	v_mul_f32_e32 v193, v193, v209
	ds_write2_b32 v218, v192, v193 offset0:192 offset1:224
	v_add_u32_e32 v218, 0x400, v12
	s_waitcnt vmcnt(6)
	v_fmac_f32_e32 v11, v194, v194
	v_mul_f32_e32 v194, v194, v210
	v_fmac_f32_e32 v11, v195, v195
	v_mul_f32_e32 v195, v195, v211
	ds_write2_b32 v218, v194, v195 offset1:32
	s_waitcnt vmcnt(4)
	v_fmac_f32_e32 v11, v196, v196
	v_mul_f32_e32 v196, v196, v212
	v_fmac_f32_e32 v11, v197, v197
	v_mul_f32_e32 v197, v197, v213
	ds_write2_b32 v218, v196, v197 offset0:64 offset1:96
	s_waitcnt vmcnt(2)
	v_fmac_f32_e32 v11, v198, v198
	v_mul_f32_e32 v198, v198, v214
	v_fmac_f32_e32 v11, v199, v199
	v_mul_f32_e32 v199, v199, v215
	ds_write2_b32 v218, v198, v199 offset0:128 offset1:160
	s_waitcnt vmcnt(0)
; template <int M> DEVI float shx(float v) { return __int_as_float(__builtin_amdgcn_ds_swizzle(__float_as_int(v), (M << 10) | 0x1f)); }
; DEVI void sk_gemm(const float* __restrict__ A, int lda, int K, const float* __restrict__ W, int N, const float* __restrict__ gain,
;                   bool use_rs, float* __restrict__ out, int ldo, int mode, unsigned char* lds, int wv, int bid, int nblk) {
;     ...
;         const int b = tid >> 5, j = tid & 31; float ss = 0.f;
; #pragma unroll 8
;         for (int k = j; k < kc; k += 32) { const float v = A[(size_t)b * lda + k0 + k]; ss += v * v; As[b * 1024 + k] = v * gain[k0 + k]; }
;         if (use_rs) { ss += shx<16>(ss); ss += shx<8>(ss); ss += shx<4>(ss); ss += shx<2>(ss); ss += shx<1>(ss); if (j == 0) rsS[b] = rsqrtf(ss / (float)K + 1e-6f); }
	v_fmac_f32_e32 v11, v200, v200
	v_mul_f32_e32 v200, v200, v216
	v_fmac_f32_e32 v11, v201, v201
	v_mul_f32_e32 v201, v201, v217
	ds_write2_b32 v218, v200, v201 offset0:192 offset1:224
	global_load_dword v186, v[14:15], off offset:2048
	global_load_dword v187, v[14:15], off offset:2176
	global_load_dword v188, v[14:15], off offset:2304
	global_load_dword v189, v[14:15], off offset:2432
	global_load_dword v190, v[14:15], off offset:2560
	global_load_dword v191, v[14:15], off offset:2688
	global_load_dword v192, v[14:15], off offset:2816
	global_load_dword v193, v[14:15], off offset:2944
	global_load_dword v194, v[14:15], off offset:3072
	global_load_dword v195, v[14:15], off offset:3200
	global_load_dword v196, v[14:15], off offset:3328
	global_load_dword v197, v[14:15], off offset:3456
	global_load_dword v198, v[14:15], off offset:3584
	global_load_dword v199, v[14:15], off offset:3712
	global_load_dword v200, v[14:15], off offset:3840
	global_load_dword v201, v[14:15], off offset:3968
	global_load_dword v202, v[16:17], off offset:2048
	global_load_dword v203, v[16:17], off offset:2176
	global_load_dword v204, v[16:17], off offset:2304
	global_load_dword v205, v[16:17], off offset:2432
	global_load_dword v206, v[16:17], off offset:2560
	global_load_dword v207, v[16:17], off offset:2688
	global_load_dword v208, v[16:17], off offset:2816
	global_load_dword v209, v[16:17], off offset:2944
	global_load_dword v210, v[16:17], off offset:3072
	global_load_dword v211, v[16:17], off offset:3200
	global_load_dword v212, v[16:17], off offset:3328
	global_load_dword v213, v[16:17], off offset:3456
	global_load_dword v214, v[16:17], off offset:3584
	global_load_dword v215, v[16:17], off offset:3712
	global_load_dword v216, v[16:17], off offset:3840
	global_load_dword v217, v[16:17], off offset:3968
	v_add_u32_e32 v218, 0x800, v12
	s_waitcnt vmcnt(14)
	v_fmac_f32_e32 v11, v186, v186
	v_mul_f32_e32 v186, v186, v202
	v_fmac_f32_e32 v11, v187, v187
	v_mul_f32_e32 v187, v187, v203
	ds_write2_b32 v218, v186, v187 offset1:32
	s_waitcnt vmcnt(12)
	v_fmac_f32_e32 v11, v188, v188
	v_mul_f32_e32 v188, v188, v204
	v_fmac_f32_e32 v11, v189, v189
	v_mul_f32_e32 v189, v189, v205
	ds_write2_b32 v218, v188, v189 offset0:64 offset1:96
	s_waitcnt vmcnt(10)
	v_fmac_f32_e32 v11, v190, v190
	v_mul_f32_e32 v190, v190, v206
	v_fmac_f32_e32 v11, v191, v191
	v_mul_f32_e32 v191, v191, v207
	ds_write2_b32 v218, v190, v191 offset0:128 offset1:160
	s_waitcnt vmcnt(8)
	v_fmac_f32_e32 v11, v192, v192
	v_mul_f32_e32 v192, v192, v208
	v_fmac_f32_e32 v11, v193, v193
	v_mul_f32_e32 v193, v193, v209
	ds_write2_b32 v218, v192, v193 offset0:192 offset1:224
	v_add_u32_e32 v218, 0xc00, v12
	s_waitcnt vmcnt(6)
	v_fmac_f32_e32 v11, v194, v194
	v_mul_f32_e32 v194, v194, v210
	v_fmac_f32_e32 v11, v195, v195
	v_mul_f32_e32 v195, v195, v211
	ds_write2_b32 v218, v194, v195 offset1:32
	s_waitcnt vmcnt(4)
	v_fmac_f32_e32 v11, v196, v196
	v_mul_f32_e32 v196, v196, v212
	v_fmac_f32_e32 v11, v197, v197
	v_mul_f32_e32 v197, v197, v213
	ds_write2_b32 v218, v196, v197 offset0:64 offset1:96
	s_waitcnt vmcnt(2)
	v_fmac_f32_e32 v11, v198, v198
	v_mul_f32_e32 v198, v198, v214
	v_fmac_f32_e32 v11, v199, v199
	v_mul_f32_e32 v199, v199, v215
	ds_write2_b32 v218, v198, v199 offset0:128 offset1:160
	s_waitcnt vmcnt(0)
	v_fmac_f32_e32 v11, v200, v200
	v_mul_f32_e32 v200, v200, v216
	v_fmac_f32_e32 v11, v201, v201
	v_mul_f32_e32 v201, v201, v217
	ds_write2_b32 v218, v200, v201 offset0:192 offset1:224
	s_or_b64 exec, exec, s[14:15]
	ds_swizzle_b32 v2, v11 offset:swizzle(SWAP,16)
	s_waitcnt lgkmcnt(0)
	v_add_f32_e32 v2, v11, v2
	ds_swizzle_b32 v3, v2 offset:swizzle(SWAP,8)
	s_waitcnt lgkmcnt(0)
	v_add_f32_e32 v2, v2, v3
	ds_swizzle_b32 v3, v2 offset:swizzle(SWAP,4)
	s_waitcnt lgkmcnt(0)
	v_add_f32_e32 v2, v2, v3
	ds_swizzle_b32 v3, v2 offset:swizzle(SWAP,2)
	s_waitcnt lgkmcnt(0)
	v_add_f32_e32 v2, v2, v3
	ds_swizzle_b32 v3, v2 offset:swizzle(SWAP,1)
	s_and_saveexec_b64 s[14:15], s[4:5]
	s_cbranch_execz .LBB0_1922
	s_waitcnt lgkmcnt(0)
	v_add_f32_e32 v2, v2, v3
	v_fmamk_f32 v2, v2, 0x3a800000, v224
	v_mul_f32_e32 v3, 0x4b800000, v2
	v_cmp_gt_f32_e32 vcc, s77, v2
	s_nop 1
	v_cndmask_b32_e32 v2, v2, v3, vcc
	v_rsq_f32_e32 v2, v2
	s_nop 0
	v_mul_f32_e32 v3, 0x45800000, v2
	v_cndmask_b32_e32 v2, v2, v3, vcc
	ds_write_b32 v39, v2
